# p4 + M1 tile groups 4 row-tiles x 32 col-tiles (XCD round 4x8 instead of 8x4)
# speedup vs baseline: 1.0045x; 1.0017x over previous
.LBB0_1154:
	s_andn2_b64 vcc, exec, s[0:1]
	s_cbranch_vccnz .LBB0_1219
	v_readlane_b32 s0, v254, 0
	v_readlane_b32 s1, v254, 1
	v_readlane_b32 s2, v254, 4
	v_mbcnt_lo_u32_b32 v0, -1, 0
	v_mbcnt_hi_u32_b32 v0, -1, v0
	s_waitcnt lgkmcnt(0)
	s_mov_b32 s15, s80
	v_readlane_b32 s2, v254, 5
	v_readlane_b32 s3, v254, 6
	s_waitcnt vmcnt(0)
	v_mov_b64_e32 v[2:3], s[0:1]
	s_load_dword s14, s[2:3], 0x0
	flat_load_dwordx2 v[140:141], v[2:3] offset:224
	v_mbcnt_lo_u32_b32 v0, -1, 0
	v_mbcnt_hi_u32_b32 v0, -1, v0
	s_cmpk_gt_i32 s15, 0x13ff
	v_add_u32_e32 v0, s81, v0
	s_nop 0
	v_readfirstlane_b32 s3, v0
	s_cbranch_scc1 .LBB0_1173
	v_bfe_i32 v2, v0, 27, 1
	v_lshlrev_b32_e32 v145, 4, v0
	v_lshrrev_b32_e32 v2, 22, v2
	v_add_u32_e32 v2, v145, v2
	v_and_b32_e32 v2, 0xfffffc00, v2
	v_sub_u32_e32 v2, v145, v2
	v_lshrrev_b32_e32 v3, 4, v2
	v_ashrrev_i32_e32 v4, 31, v0
	v_bitop3_b32 v2, v3, v2, 32 bitop3:0x6c
	v_lshrrev_b32_e32 v4, 26, v4
	v_ashrrev_i32_e32 v3, 31, v2
	v_add_u32_e32 v4, v0, v4
	v_lshrrev_b32_e32 v3, 26, v3
	v_ashrrev_i32_e32 v146, 6, v4
	s_mov_b64 s[0:1], 0x2200000
	v_add_u32_e32 v3, v2, v3
	v_lshlrev_b32_e32 v4, 3, v146
	s_waitcnt vmcnt(0) lgkmcnt(0)
	v_lshl_add_u64 v[130:131], v[140:141], 0, s[0:1]
	s_mov_b64 s[0:1], 0x8200000
	v_ashrrev_i32_e32 v144, 6, v3
	v_and_b32_e32 v4, -16, v4
	v_lshl_add_u64 v[132:133], v[140:141], 0, s[0:1]
	v_add_u32_e32 v4, v144, v4
	v_and_b32_e32 v5, 3, v144
	s_mov_b32 s0, 0xfffe0
	s_ashr_i32 s17, s15, 31
	v_and_or_b32 v5, v4, s0, v5
	s_lshr_b32 s0, s17, 29
	s_add_i32 s0, s15, s0
	s_ashr_i32 s4, s3, 6
	s_ashr_i32 s1, s0, 3
	s_and_b32 s0, s0, -8
	s_ashr_i32 s5, s3, 8
	s_lshl_b32 s16, s4, 10
	s_sub_i32 s0, s15, s0
	s_cmp_lt_i32 s0, 0
	s_movk_i32 s2, 0x281
	s_cselect_b32 s2, s2, 0x280
	s_mul_i32 s0, s0, s2
	s_add_i32 s0, s0, s1
	s_ashr_i32 s1, s0, 31
	s_lshr_b32 s1, s1, 25
	s_add_i32 s1, s0, s1
	s_ashr_i32 s2, s1, 7
	s_and_b32 s1, s1, 0xff80
	s_sub_i32 s0, s0, s1
	s_sext_i32_i16 s1, s0
	s_bfe_u32 s1, s1, 0x2001e
	s_add_i32 s1, s0, s1
	v_lshrrev_b32_e32 v6, 2, v4
	v_lshlrev_b32_e32 v7, 1, v4
	v_and_b32_e32 v3, 0xc0, v3
	s_lshl_b32 s6, s2, 2
	s_sext_i32_i16 s2, s1
	s_and_b32 s1, s1, 0xfffc
	v_and_b32_e32 v6, 4, v6
	v_and_b32_e32 v7, 24, v7
	v_sub_u32_e32 v2, v2, v3
	s_sub_i32 s0, s0, s1
	v_or3_b32 v5, v5, v6, v7
	v_lshlrev_b32_e32 v6, 5, v146
	v_ashrrev_i16_sdwa v2, v241, sext(v2) dst_sel:DWORD dst_unused:UNUSED_PAD src0_sel:DWORD src1_sel:BYTE_0
	s_lshr_b32 s2, s2, 2
	s_sext_i32_i16 s0, s0
	v_and_b32_e32 v6, 32, v6
	v_bfe_i32 v147, v2, 0, 16
	s_add_i32 s10, s6, s0
	s_bfe_i64 s[6:7], s[2:3], 0x100000
	v_add_lshl_u32 v2, v6, v147, 1
	s_lshl_b64 s[6:7], s[6:7], 20
	v_lshl_add_u32 v134, v5, 12, v2
	v_lshl_add_u64 v[148:149], v[130:131], 0, s[6:7]
	v_mov_b32_e32 v135, v1
	s_add_i32 s18, s16, 0
	v_lshl_add_u64 v[138:139], v[148:149], 0, v[134:135]
	s_add_i32 m0, s18, 0x10000
	v_lshl_add_u32 v136, v4, 12, v2
	s_ashr_i32 s11, s10, 31
	global_load_lds_dwordx4 v[138:139], off
	v_lshl_add_u64 v[142:143], v[138:139], 0, s[52:53]
	s_add_i32 m0, s18, 0x12000
	s_lshl_b64 s[0:1], s[10:11], 20
	global_load_lds_dwordx4 v[142:143], off
	v_lshl_add_u64 v[142:143], v[138:139], 0, s[54:55]
	s_add_i32 m0, s18, 0x14000
	v_lshl_add_u64 v[150:151], v[132:133], 0, s[0:1]
	global_load_lds_dwordx4 v[142:143], off
	v_lshl_add_u64 v[142:143], v[138:139], 0, s[56:57]
	s_add_i32 m0, s18, 0x16000
	v_mov_b32_e32 v137, v1
	global_load_lds_dwordx4 v[142:143], off
	v_lshl_add_u64 v[142:143], v[150:151], 0, v[136:137]
	s_mov_b32 m0, s18
	s_add_i32 s19, s18, 0x2000
	global_load_lds_dwordx4 v[142:143], off
	v_lshl_add_u64 v[152:153], v[142:143], 0, s[52:53]
	s_mov_b32 m0, s19
	s_add_i32 s20, s18, 0x4000
	global_load_lds_dwordx4 v[152:153], off
	v_lshl_add_u64 v[152:153], v[142:143], 0, s[54:55]
	s_mov_b32 m0, s20
	s_add_i32 s21, s18, 0x6000
	global_load_lds_dwordx4 v[152:153], off
	v_lshl_add_u64 v[152:153], v[142:143], 0, s[56:57]
	s_mov_b32 m0, s21
	s_cmp_eq_u32 s5, 1
	global_load_lds_dwordx4 v[152:153], off
	s_cselect_b64 s[0:1], -1, 0
	s_cmp_lg_u32 s5, 1
	s_cbranch_scc1 .LBB0_1158
	s_barrier

.LBB0_1161:
	s_add_i32 s25, s25, 1
	s_mul_i32 s4, s25, s24
	s_mul_hi_u32 s5, s25, s14
	s_add_i32 s5, s5, s4
	s_mul_i32 s4, s25, s14
	s_add_u32 s12, s4, s15
	s_addc_u32 s13, s5, s17
	v_mov_b64_e32 v[144:145], 0x1400
	v_cmp_lt_i64_e64 s[4:5], s[12:13], v[144:145]
	v_mov_b64_e32 v[144:145], 0x13ff
	v_cmp_gt_i64_e32 vcc, s[12:13], v[144:145]
	s_cbranch_vccnz .LBB0_1163
	s_ashr_i32 s6, s12, 31
	s_lshr_b32 s6, s6, 29
	s_add_i32 s6, s12, s6
	s_ashr_i32 s7, s6, 3
	s_and_b32 s6, s6, -8
	s_sub_i32 s6, s12, s6
	s_cmp_lt_i32 s6, 0
	s_movk_i32 s8, 0x281
	s_cselect_b32 s8, s8, 0x280
	s_mul_i32 s6, s6, s8
	s_add_i32 s6, s6, s7
	s_ashr_i32 s7, s6, 31
	s_lshr_b32 s7, s7, 25
	s_add_i32 s7, s6, s7
	s_ashr_i32 s8, s7, 7
	s_lshl_b32 s8, s8, 2
	s_and_b32 s7, s7, 0xffffff80
	s_sub_i32 s7, s6, s7
	s_lshr_b32 s6, s7, 2
	s_and_b32 s7, s7, 3
	s_add_i32 s8, s8, s7
